# DQK=64: first two K-fragment LDS reads of each tile issued right after the barrier, ahead of the loop-edge scalar code
# speedup vs baseline: 1.0059x; 1.0034x over previous
; template <bool FIRST> __device__ __forceinline__ void partialSM(f32x16& p0, f32x16& p1, float& m_reg, float& alpha, f32x16& negm, float c_cur) {
;   float pmax = p0[0];
; #pragma unroll
;   for (int r = 1; r < 16; ++r) pmax = fmaxf(pmax, p0[r]);
; #pragma unroll
;   for (int r = 0; r < 16; ++r) pmax = fmaxf(pmax, p1[r]);
;   { auto rr = __builtin_amdgcn_permlane32_swap(__float_as_uint(pmax), __float_as_uint(pmax), false, false);
;     pmax = fmaxf(__uint_as_float(rr[0]), __uint_as_float(rr[1])); }
;   alpha = 1.f;
;   if (FIRST || !__builtin_expect(__all(pmax <= THR2), 1)) {
;     const float d = FIRST ? pmax : fmaxf(pmax, 0.f); m_reg += d; if (!FIRST) alpha = __builtin_amdgcn_exp2f(-d);
; #pragma unroll
;     for (int r = 0; r < 16; ++r) { p0[r] -= d; p1[r] -= d; }
;     const float nm = c_cur - m_reg;
; #pragma unroll
;     for (int r = 0; r < 16; ++r) negm[r] = nm;
;   }
; #pragma unroll
;   for (int r = 0; r < 16; ++r) p0[r] = __builtin_amdgcn_exp2f(p0[r]);
; template <int DQK, bool BIAS, bool VIRT = false>
; __device__ __forceinline__ void attn_pass(const bf16_t* __restrict__ Qb, const bf16_t* __restrict__ Kh, const bf16_t* __restrict__ Vh, int L, int NT, int qw0, const float* lut, f32x16 (&o)[4], char* lds, int nact) {
;     ...
;   const int sr = tid >> 4, sc = (tid & 15) * 8, vst0 = v_st(sr, sc), vst1 = v_st(32 + sr, sc);
;   const int kr = tid >> 3, kc = (tid & 7) * 8;
;   const int vb0 = (int)(uintptr_t)V_lds + v_rd_base(lane);
;   constexpr int SDEPTH = DQK == 128 ? 1 : 2;
;   struct { bf16x8 vs0, vs1, ks0, ks1; } sr_[SDEPTH];
;     ...
;   f32x16 pA0, pA1, pB0, pB1; float alA, alB; bf16x8 pa0, pa1, pa2, pa3;
;   constexpr int SE = 0, SO = SDEPTH - 1;
;   if (wid >= nact) {
;     SLOAD(SE, 0); asm volatile("s_waitcnt vmcnt(0)" ::: "memory"); SWRITE(0, SE); __syncthreads();
;     SLOAD(SO, KVBLK); if (SDEPTH == 2) { if (2 < NT) SLOAD(SE, 2 * KVBLK); }
;     SWAIT(); SWRITE(1, SO); __syncthreads();
;     for (int j = 1; j + 1 < NT; j += 2) {
;       SLOAD(SO, (j + SDEPTH) * KVBLK); __syncthreads(); SWAIT(); SWRITE(0, SE); __syncthreads();
;       if (SDEPTH == 1 || j + 3 < NT) SLOAD(SE, (j + 1 + SDEPTH) * KVBLK);
;       __syncthreads(); SWAIT(); SWRITE(1, SO); __syncthreads();
;     }
;     __syncthreads();
;     return;
;   }
;     ...
;   SLOAD(SE, 0); asm volatile("s_waitcnt vmcnt(0)" ::: "memory"); SWRITE(0, SE); __syncthreads();
.LBB0_215:
	v_and_b32_e32 v62, 63, v90
	v_lshlrev_b32_e32 v39, 4, v62
	v_lshlrev_b32_e32 v38, 3, v62
	v_and_b32_e32 v39, 0xc0, v39
	v_lshlrev_b32_e32 v40, 1, v62
	v_and_or_b32 v39, v38, 24, v39
	v_and_b32_e32 v40, 32, v40
	v_and_b32_e32 v38, 0x100, v38
	v_or3_b32 v63, v39, v40, v38
	v_max_f32_e32 v38, v19, v19
	v_max_f32_e32 v39, v18, v18
	v_max_f32_e32 v38, v39, v38
	v_max3_f32 v38, v38, v20, v21
	v_max3_f32 v38, v38, v22, v23
	v_max3_f32 v38, v38, v24, v25
	v_max3_f32 v38, v38, v26, v27
	v_max3_f32 v38, v38, v28, v29
	v_max3_f32 v38, v38, v30, v31
	v_max3_f32 v38, v38, v32, v33
	v_max3_f32 v64, v38, v2, v3
	v_max3_f32 v64, v64, v4, v5
	v_max3_f32 v64, v64, v6, v7
	v_max3_f32 v64, v64, v8, v9
	v_max3_f32 v64, v64, v10, v11
	v_max3_f32 v64, v64, v12, v13
	v_max3_f32 v64, v64, v14, v15
	v_max3_f32 v64, v64, v16, v17
	v_mov_b32_e32 v65, v64
	v_mad_i64_i32 v[54:55], s[8:9], v91, s33, 0
	v_mad_i64_i32 v[56:57], s[8:9], v92, s33, 0
	s_cmp_lg_u32 0, -1
	v_permlane32_swap_b32_e32 v64, v65
	s_cselect_b32 s19, 0, 0
	s_and_b32 s8, s18, 0x3fffffc0
	v_max_f32_e32 v65, v65, v65
	v_max_f32_e32 v64, v64, v64
	s_lshl_b32 s8, s8, 2
	v_mov_b64_e32 v[58:59], s[14:15]
	v_mov_b64_e32 v[60:61], s[6:7]
	v_max_f32_e32 v64, v64, v65
	s_add_i32 s24, s8, 0
	v_mad_i64_i32 v[38:39], s[8:9], v89, s33, v[58:59]
	v_mad_i64_i32 v[40:41], s[8:9], v87, s33, v[58:59]
	v_mad_i64_i32 v[46:47], s[6:7], v88, s33, v[60:61]
	v_sub_f32_e32 v101, v3, v64
	v_sub_f32_e32 v100, v2, v64
	v_mad_i64_i32 v[2:3], s[6:7], v86, s33, v[60:61]
	v_lshl_add_u64 v[38:39], v[38:39], 0, v[0:1]
	v_lshl_add_u64 v[42:43], v[40:41], 0, v[0:1]
	v_lshl_add_u64 v[46:47], v[46:47], 0, v[36:37]
	v_lshl_add_u64 v[2:3], v[2:3], 0, v[36:37]
	global_load_dwordx4 v[38:41], v[38:39], off
	s_nop 0
	global_load_dwordx4 v[42:45], v[42:43], off
	v_sub_f32_e32 v103, v5, v64
	global_load_dwordx4 v[46:49], v[46:47], off offset:2048
	v_sub_f32_e32 v102, v4, v64
	global_load_dwordx4 v[174:177], v[2:3], off offset:2048
	v_mad_i64_i32 v[2:3], s[6:7], v53, s33, v[58:59]
	v_lshl_add_u64 v[2:3], v[2:3], 0, v[0:1]
	v_mad_i64_i32 v[4:5], s[6:7], v52, s33, v[58:59]
	v_lshl_add_u64 v[4:5], v[4:5], 0, v[0:1]
	global_load_dwordx4 v[170:173], v[2:3], off
	global_load_dwordx4 v[166:169], v[4:5], off
	v_add_lshl_u32 v0, s29, v34, 2
	v_add_u32_e32 v223, s19, v63
	s_add_i32 s24, s24, 0x10000
	s_addk_i32 s19, 0x4000
	v_sub_u32_e32 v0, v190, v0
	s_add_i32 s6, 0, 0x10c80
	v_sub_f32_e32 v18, v18, v64
	v_sub_f32_e32 v19, v19, v64
	v_sub_f32_e32 v20, v20, v64
	v_sub_f32_e32 v21, v21, v64
	v_sub_f32_e32 v22, v22, v64
	v_sub_f32_e32 v23, v23, v64
	v_sub_f32_e32 v24, v24, v64
	v_sub_f32_e32 v25, v25, v64
	v_sub_f32_e32 v26, v26, v64
	v_sub_f32_e32 v27, v27, v64
	v_sub_f32_e32 v28, v28, v64
	v_sub_f32_e32 v29, v29, v64
	v_sub_f32_e32 v30, v30, v64
	v_sub_f32_e32 v31, v31, v64
	v_sub_f32_e32 v32, v32, v64
	v_sub_f32_e32 v33, v33, v64
	v_add_u32_e32 v67, s6, v0
	v_lshlrev_b32_e32 v0, 4, v51
	s_add_u32 s4, s36, s4
	v_exp_f32_e32 v148, v18
	v_exp_f32_e32 v178, v19
	v_exp_f32_e32 v146, v20
	v_exp_f32_e32 v149, v21
	v_exp_f32_e32 v144, v22
	v_exp_f32_e32 v147, v23
	v_exp_f32_e32 v143, v24
	v_exp_f32_e32 v145, v25
	v_exp_f32_e32 v137, v26
	v_exp_f32_e32 v139, v27
	v_exp_f32_e32 v136, v28
	v_exp_f32_e32 v138, v29
	v_exp_f32_e32 v135, v30
	v_exp_f32_e32 v142, v31
	v_exp_f32_e32 v140, v32
	v_exp_f32_e32 v141, v33
	v_lshl_add_u64 v[2:3], v[56:57], 0, v[0:1]
	s_addc_u32 s5, s37, s5
	v_lshlrev_b32_e32 v0, 4, v50
	v_add_f32_e32 v233, 0, v64
	v_sub_f32_e32 v113, v15, v64
	v_sub_f32_e32 v112, v14, v64
	s_waitcnt vmcnt(3)
	v_lshl_add_u64 v[192:193], s[4:5], 0, v[2:3]
	v_lshl_add_u64 v[2:3], v[54:55], 0, v[0:1]
	v_mov_b32_e32 v14, v1
	v_mov_b32_e32 v15, v1
	v_sub_f32_e32 v115, v17, v64
	v_sub_f32_e32 v114, v16, v64
	v_sub_f32_e32 v111, v13, v64
	v_sub_f32_e32 v110, v12, v64
	v_sub_f32_e32 v109, v11, v64
	v_sub_f32_e32 v108, v10, v64
	v_sub_f32_e32 v107, v9, v64
	v_sub_f32_e32 v106, v8, v64
	v_sub_f32_e32 v105, v7, v64
	v_sub_f32_e32 v104, v6, v64
	v_sub_f32_e32 v132, v66, v233
	s_waitcnt vmcnt(5)
	ds_write_b128 v212, v[38:41] offset:16384
	s_waitcnt vmcnt(4)
	ds_write_b128 v213, v[42:45] offset:16384
	s_waitcnt vmcnt(3)
	ds_write_b128 v229, v[46:49] offset:49152
	v_lshlrev_b32_e32 v224, 2, v35
	v_cmp_gt_u32_e64 s[40:41], 32, v62
	v_lshl_add_u32 v191, v34, 2, s24
	v_add_u32_e32 v211, s19, v63
	v_lshl_add_u64 v[194:195], s[36:37], 0, v[2:3]
	v_mov_b32_e32 v0, v1
	v_mov_b32_e32 v2, v1
	v_mov_b32_e32 v3, v1
	v_mov_b32_e32 v4, v1
	v_mov_b32_e32 v5, v1
	v_mov_b32_e32 v6, v1
	v_mov_b32_e32 v7, v1
	v_mov_b32_e32 v8, v1
	v_mov_b32_e32 v9, v1
	v_mov_b32_e32 v10, v1
	v_mov_b32_e32 v11, v1
	v_mov_b32_e32 v12, v1
	v_mov_b32_e32 v13, v1
	v_mov_b32_e32 v210, 0
	v_mov_b64_e32 v[64:65], v[14:15]
	v_mov_b64_e32 v[48:49], v[14:15]
	v_mov_b64_e32 v[32:33], v[14:15]
	s_mov_b32 s25, 2
	s_mov_b32 s18, 64
	v_mov_b32_e32 v230, 1.0
	v_mov_b64_e32 v[62:63], v[12:13]
	v_mov_b64_e32 v[60:61], v[10:11]
	v_mov_b64_e32 v[58:59], v[8:9]
	v_mov_b64_e32 v[56:57], v[6:7]
	v_mov_b64_e32 v[54:55], v[4:5]
	v_mov_b64_e32 v[52:53], v[2:3]
	v_mov_b64_e32 v[50:51], v[0:1]
	v_mov_b64_e32 v[46:47], v[12:13]
	v_mov_b64_e32 v[44:45], v[10:11]
	v_mov_b64_e32 v[42:43], v[8:9]
	v_mov_b64_e32 v[40:41], v[6:7]
	v_mov_b64_e32 v[38:39], v[4:5]
	v_mov_b64_e32 v[36:37], v[2:3]
	v_mov_b64_e32 v[34:35], v[0:1]
	v_mov_b64_e32 v[30:31], v[12:13]
	v_mov_b64_e32 v[28:29], v[10:11]
	v_mov_b64_e32 v[26:27], v[8:9]
	v_mov_b64_e32 v[24:25], v[6:7]
	v_mov_b64_e32 v[22:23], v[4:5]
	v_mov_b64_e32 v[20:21], v[2:3]
	v_mov_b64_e32 v[18:19], v[0:1]
	v_mov_b32_e32 v2, 0
	v_mov_b32_e32 v3, v210
	v_mov_b32_e32 v4, v210
	v_mov_b32_e32 v5, v210
	v_mov_b32_e32 v6, v210
	v_mov_b32_e32 v7, v210
	v_mov_b32_e32 v8, v210
	v_mov_b32_e32 v9, v210
	v_mov_b32_e32 v10, v210
	v_mov_b32_e32 v11, v210
	v_mov_b32_e32 v12, v210
	v_mov_b32_e32 v13, v210
	v_mov_b32_e32 v14, v210
	v_mov_b32_e32 v15, v210
	v_mov_b32_e32 v16, v210
	v_mov_b32_e32 v17, v210
	v_mov_b32_e32 v196, v132
	v_mov_b32_e32 v197, v132
	v_mov_b32_e32 v237, v132
	v_mov_b32_e32 v238, v132
	v_mov_b32_e32 v239, v132
	v_mov_b32_e32 v240, v132
	v_mov_b32_e32 v241, v132
	v_mov_b32_e32 v242, v132
	v_mov_b32_e32 v243, v132
	v_mov_b32_e32 v244, v132
	v_mov_b32_e32 v245, v132
	v_mov_b32_e32 v246, v132
	v_mov_b32_e32 v247, v132
	v_mov_b32_e32 v248, v132
	v_mov_b32_e32 v249, v132
	v_mov_b32_e32 v236, v132
	v_mov_b32_e32 v250, v132
	v_mov_b32_e32 v251, v132
	s_waitcnt lgkmcnt(0)
	s_barrier
	ds_read_b128 v[180:183], v225 offset:53248
	ds_read_b128 v[116:119], v225 offset:49152
	s_add_i32 s19, s11, s18
	s_sub_i32 s4, s19, 31
	s_cmpk_lt_i32 s4, 0x80
	s_cbranch_scc1 .LBB0_249
; #define SBAR() __builtin_amdgcn_sched_barrier(0)
; #define SLOAD(i, k0) do { sr_[i].vs0 = GLD8(&Vh[(long)((k0) + sr) * LD + sc]); sr_[i].vs1 = GLD8(&Vh[(long)((k0) + 32 + sr) * LD + sc]); \
;     if (DQK == 128) { sr_[i].ks0 = GLD8(&Kh[(long)((k0) + sr) * LD + sc]); sr_[i].ks1 = GLD8(&Kh[(long)((k0) + 32 + sr) * LD + sc]); } \
;     else { sr_[i].ks0 = GLD8(&Kh[(long)((k0) + kr) * LD + kc]); } } while (0)
; #define SWAIT() do { if (SDEPTH == 1) asm volatile("s_waitcnt vmcnt(0)" ::: "memory"); else if (DQK == 128) asm volatile("s_waitcnt vmcnt(4)" ::: "memory"); else asm volatile("s_waitcnt vmcnt(3)" ::: "memory"); } while (0)
; template <int DQK> __device__ __forceinline__ void qkt(f32x16& p0, f32x16& p1, const char* Ks, const bf16x8* qr, int r32, int hi, const f32x16& negm) {
; #pragma unroll
;   for (int d0 = 0; d0 < DQK / 16; ++d0) { const int cb = (d0 * 16 + hi * 8) * 2;
;     const bf16x8 b0 = *reinterpret_cast<const bf16x8*>(Ks + (DQK == 128 ? KSWZ(r32, cb) : KSWZ64(r32, cb)));
;     const bf16x8 b1 = *reinterpret_cast<const bf16x8*>(Ks + (DQK == 128 ? KSWZ(32 + r32, cb) : KSWZ64(32 + r32, cb)));
;     if (d0 == 0) { p0 = __builtin_amdgcn_mfma_f32_32x32x16_bf16(b0, qr[0], negm, 0, 0, 0); p1 = __builtin_amdgcn_mfma_f32_32x32x16_bf16(b1, qr[0], negm, 0, 0, 0); }
;     else { p0 = __builtin_amdgcn_mfma_f32_32x32x16_bf16(b0, qr[d0], p0, 0, 0, 0); p1 = __builtin_amdgcn_mfma_f32_32x32x16_bf16(b1, qr[d0], p1, 0, 0, 0); } }
; }
; template <int DQK, bool BIAS, bool VIRT = false>
; __device__ __forceinline__ void attn_pass(const bf16_t* __restrict__ Qb, const bf16_t* __restrict__ Kh, const bf16_t* __restrict__ Vh, int L, int NT, int qw0, const float* lut, f32x16 (&o)[4], char* lds, int nact) {
;     ...
;   SLOAD(SE, 0); asm volatile("s_waitcnt vmcnt(0)" ::: "memory"); SWRITE(0, SE); __syncthreads();
;   qkt<DQK>(pA0, pA1, K_lds, qr, r32, hi, negm); fixup<BIAS, VIRT>(pA0, pA1, 0, L, qw0, r32, hi, lut); partialSM<true>(pA0, pA1, m_reg, alA, negm, c_cur);
;   SLOAD(SO, KVBLK); if (SDEPTH == 2) { if (2 < NT) SLOAD(SE, 2 * KVBLK); }
;   SWAIT(); SWRITE(1, SO); __syncthreads();
;   for (int j = 1; j + 1 < NT; j += 2) {
;     NEGM(j); SBAR(); qkt<DQK>(pB0, pB1, K_lds + SHM_K, qr, r32, hi, negm);
;     finishSM(pA0, pA1, alA, l_reg, pa0, pa1, pa2, pa3); SBAR();
.LBB0_216:
.LBB0_217:
	v_mov_b32_e32 v0, s39
	ds_read_b32 v133, v0
.LBB0_218:
	s_add_i32 s99, s19, 0xffffff61
	s_cmp_lt_u32 s99, 0xfffffea3
	s_cbranch_scc0 .Lold_h1
	s_cmp_le_u32 s18, s47
	s_cbranch_scc0 .Lold_h1
	ds_read_b128 v[184:187], v227 offset:53248
	ds_read_b128 v[68:71], v227 offset:49152
	ds_read_b128 v[72:75], v228 offset:53248
	ds_read_b128 v[206:209], v228 offset:49152
	s_waitcnt lgkmcnt(4)
	v_cmp_neq_f32_e32 vcc, v133, v66
	s_cbranch_vccnz .Lcupd_f1
.Lcret_f1:
	v_mfma_f32_32x32x16_bf16 v[84:99], v[116:119], v[162:165], v[236:251]
	v_mfma_f32_32x32x16_bf16 v[116:131], v[180:183], v[162:165], v[236:251]
	ds_read_b128 v[180:183], v226 offset:53248
	v_add_f32_e32 v0, 0, v148
	v_add_f32_e32 v0, v178, v0
	v_add_f32_e32 v0, v146, v0
	v_add_f32_e32 v0, v149, v0
	v_add_f32_e32 v0, v144, v0
	v_add_f32_e32 v0, v147, v0
	v_add_f32_e32 v0, v143, v0
	v_add_f32_e32 v0, v145, v0
	v_add_f32_e32 v0, v137, v0
	v_add_f32_e32 v0, v139, v0
	s_waitcnt lgkmcnt(3)
	v_mfma_f32_32x32x16_bf16 v[116:131], v[184:187], v[158:161], v[116:131]
	v_add_f32_e32 v0, v136, v0
	v_add_f32_e32 v0, v138, v0
	v_add_f32_e32 v0, v135, v0
	v_add_f32_e32 v0, v142, v0
	v_add_f32_e32 v0, v140, v0
	v_add_f32_e32 v0, v141, v0
	v_mfma_f32_32x32x16_bf16 v[84:99], v[68:71], v[158:161], v[84:99]
	ds_read_b128 v[184:187], v226 offset:49152
	v_cvt_pk_bf16_f32 v76, v148, v178
	v_cvt_pk_bf16_f32 v77, v146, v149
	v_cvt_pk_bf16_f32 v78, v144, v147
	v_cvt_pk_bf16_f32 v79, v143, v145
	v_lshl_add_u64 v[148:149], v[194:195], 0, s[0:1]
	v_lshl_add_u64 v[196:197], v[192:193], 0, s[0:1]
	s_waitcnt lgkmcnt(2)
	v_mfma_f32_32x32x16_bf16 v[116:131], v[72:75], v[154:157], v[116:131]
	v_cvt_pk_bf16_f32 v80, v137, v139
	v_cvt_pk_bf16_f32 v81, v136, v138
	v_cvt_pk_bf16_f32 v82, v135, v142
	v_cvt_pk_bf16_f32 v83, v140, v141
	s_mov_b32 s4, 0x102b1000
	v_add_co_u32_e64 v132, s[4:5], s4, v148
	v_mfma_f32_32x32x16_bf16 v[84:99], v[206:209], v[154:157], v[84:99]
	ds_read_b64_tr_b16 v[134:135], v223 offset:0
	ds_read_b64_tr_b16 v[136:137], v223 offset:0x800
	ds_read_b64_tr_b16 v[138:139], v223 offset:0x200
	ds_read_b64_tr_b16 v[140:141], v223 offset:0xa00
	ds_read_b64_tr_b16 v[142:143], v223 offset:0x400
	ds_read_b64_tr_b16 v[144:145], v223 offset:0xc00
	ds_read_b64_tr_b16 v[198:199], v223 offset:0x600
	ds_read_b64_tr_b16 v[200:201], v223 offset:0xe00
	v_permlane32_swap_b32_e32 v76, v78
	v_permlane32_swap_b32_e32 v77, v79
	v_addc_co_u32_e64 v133, s[4:5], 0, v149, s[4:5]
	s_mov_b32 s4, 0x102f9000
	v_add_co_u32_e64 v202, s[4:5], s4, v148
	s_waitcnt lgkmcnt(8)
	v_mfma_f32_32x32x16_bf16 v[116:131], v[180:183], v[150:153], v[116:131]
	v_addc_co_u32_e64 v203, s[4:5], 0, v149, s[4:5]
	s_mov_b32 s4, 0x102b0000
	v_add_co_u32_e64 v204, s[4:5], s4, v196
	v_permlane32_swap_b32_e32 v80, v82
	v_permlane32_swap_b32_e32 v81, v83
	v_mfma_f32_32x32x16_bf16 v[84:99], v[184:187], v[150:153], v[84:99]
	v_addc_co_u32_e64 v205, s[4:5], 0, v197, s[4:5]
	global_load_dwordx4 v[178:181], v[132:133], off
	global_load_dwordx4 v[182:185], v[202:203], off
	global_load_dwordx4 v[186:189], v[204:205], off offset:2048
	s_waitcnt lgkmcnt(6)
	v_mfma_f32_32x32x16_bf16 v[50:65], v[76:79], v[134:137], v[50:65]
	ds_read_b64_tr_b16 v[134:135], v223 offset:0x1000
	ds_read_b64_tr_b16 v[136:137], v223 offset:0x1800
	v_exp_f32_e32 v68, v100
	v_exp_f32_e32 v69, v101
	v_add_f32_e32 v0, v68, v0
	s_waitcnt lgkmcnt(6)
	v_mfma_f32_32x32x16_bf16 v[34:49], v[76:79], v[138:141], v[34:49]
	ds_read_b64_tr_b16 v[138:139], v223 offset:0x1200
	ds_read_b64_tr_b16 v[140:141], v223 offset:0x1a00
	v_exp_f32_e32 v70, v102
	v_add_f32_e32 v0, v69, v0
	v_exp_f32_e32 v71, v103
	v_add_f32_e32 v0, v70, v0
	s_waitcnt lgkmcnt(6)
	v_mfma_f32_32x32x16_bf16 v[18:33], v[76:79], v[142:145], v[18:33]
	ds_read_b64_tr_b16 v[142:143], v223 offset:0x1400
	ds_read_b64_tr_b16 v[144:145], v223 offset:0x1c00
	v_exp_f32_e32 v72, v104
	v_add_f32_e32 v0, v71, v0
	v_exp_f32_e32 v73, v105
	v_add_f32_e32 v0, v72, v0
	s_waitcnt lgkmcnt(6)
; __device__ __forceinline__ void finishSM(f32x16& p0, f32x16& p1, float alpha, float& l_reg, bf16x8& pa0, bf16x8& pa1, bf16x8& pa2, bf16x8& pa3) {
;     ...
;   for (int r = 0; r < 16; ++r) p1[r] = __builtin_amdgcn_exp2f(p1[r]);
;   float ps = 0;
; #pragma unroll
;   for (int r = 0; r < 16; ++r) ps += p0[r];
; #pragma unroll
;   for (int r = 0; r < 16; ++r) ps += p1[r];
;   { auto rr = __builtin_amdgcn_permlane32_swap(__float_as_uint(ps), __float_as_uint(ps), false, false);
;     ps = __uint_as_float(rr[0]) + __uint_as_float(rr[1]); }
;   l_reg = l_reg * alpha + ps;
;     ...
;   PK4(p0, 0, pa0); PK4(p0, 8, pa1); PK4(p1, 0, pa2); PK4(p1, 8, pa3);
;     ...
; }
; template <int DQK> __device__ __forceinline__ void qkt(f32x16& p0, f32x16& p1, const char* Ks, const bf16x8* qr, int r32, int hi, const f32x16& negm) {
; #pragma unroll
;   for (int d0 = 0; d0 < DQK / 16; ++d0) { const int cb = (d0 * 16 + hi * 8) * 2;
;     const bf16x8 b0 = *reinterpret_cast<const bf16x8*>(Ks + (DQK == 128 ? KSWZ(r32, cb) : KSWZ64(r32, cb)));
;     const bf16x8 b1 = *reinterpret_cast<const bf16x8*>(Ks + (DQK == 128 ? KSWZ(32 + r32, cb) : KSWZ64(32 + r32, cb)));
;     if (d0 == 0) { p0 = __builtin_amdgcn_mfma_f32_32x32x16_bf16(b0, qr[0], negm, 0, 0, 0); p1 = __builtin_amdgcn_mfma_f32_32x32x16_bf16(b1, qr[0], negm, 0, 0, 0); }
;     else { p0 = __builtin_amdgcn_mfma_f32_32x32x16_bf16(b0, qr[d0], p0, 0, 0, 0); p1 = __builtin_amdgcn_mfma_f32_32x32x16_bf16(b1, qr[d0], p1, 0, 0, 0); } }
; }
; __device__ __forceinline__ int v_st(int k, int c) { const int kk = (k & ~0xC) | ((k & 4) << 1) | ((k & 8) >> 1); return ((kk >> 3) * 4 + (c >> 5)) * 512 + ((kk & 7) * 32 + (c & 31)) * 2; }
; __device__ __forceinline__ int v_rd_base(int lane) { return ((lane & 3) << 3) | (((lane >> 2) & 3) << 6) | (((lane >> 4) & 1) << 5) | (((lane >> 5) & 1) << 8); }
; template <int OFF> __device__ __forceinline__ s16x4 tr_read(int vb) {
;   s16x4 r; asm volatile("ds_read_b64_tr_b16 %0, %1 offset:%2" : "=&v"(r) : "v"(vb), "i"(OFF) : "memory"); return r;
; }
; template <int D0> __device__ __forceinline__ void pv_one(f32x16& od, int vb, bf16x8 pa0, bf16x8 pa1, bf16x8 pa2, bf16x8 pa3) {
;   const s16x4 l0 = tr_read<v_rd_off(D0, 0, 0)>(vb), h0 = tr_read<v_rd_off(D0, 0, 1)>(vb), l1 = tr_read<v_rd_off(D0, 1, 0)>(vb), h1 = tr_read<v_rd_off(D0, 1, 1)>(vb);
	v_mfma_f32_32x32x16_bf16 v[2:17], v[76:79], v[198:201], v[2:17]
	ds_read_b64_tr_b16 v[198:199], v223 offset:0x1600
	ds_read_b64_tr_b16 v[200:201], v223 offset:0x1e00
	v_exp_f32_e32 v74, v106
	v_add_f32_e32 v0, v73, v0
	v_exp_f32_e32 v75, v107
	v_add_f32_e32 v0, v74, v0
	v_add_f32_e32 v0, v75, v0
	s_waitcnt lgkmcnt(6)
	v_mfma_f32_32x32x16_bf16 v[50:65], v[80:83], v[134:137], v[50:65]
	ds_read_b64_tr_b16 v[134:135], v223 offset:0x2000
	ds_read_b64_tr_b16 v[136:137], v223 offset:0x2800
	v_cvt_pk_bf16_f32 v100, v68, v69
	v_cvt_pk_bf16_f32 v101, v70, v71
	v_cvt_pk_bf16_f32 v102, v72, v73
	v_cvt_pk_bf16_f32 v103, v74, v75
	s_waitcnt lgkmcnt(6)
	v_mfma_f32_32x32x16_bf16 v[34:49], v[80:83], v[138:141], v[34:49]
	ds_read_b64_tr_b16 v[138:139], v223 offset:0x2200
	ds_read_b64_tr_b16 v[140:141], v223 offset:0x2a00
	v_exp_f32_e32 v68, v108
	v_exp_f32_e32 v69, v109
	v_permlane32_swap_b32_e32 v100, v102
	v_permlane32_swap_b32_e32 v101, v103
	s_waitcnt lgkmcnt(6)
	v_mfma_f32_32x32x16_bf16 v[18:33], v[80:83], v[142:145], v[18:33]
	ds_read_b64_tr_b16 v[142:143], v223 offset:0x2400
	ds_read_b64_tr_b16 v[144:145], v223 offset:0x2c00
	v_exp_f32_e32 v70, v110
	v_exp_f32_e32 v71, v111
	v_exp_f32_e32 v72, v112
	s_waitcnt lgkmcnt(6)
	v_mfma_f32_32x32x16_bf16 v[2:17], v[80:83], v[198:201], v[2:17]
	ds_read_b64_tr_b16 v[198:199], v223 offset:0x2600
	ds_read_b64_tr_b16 v[200:201], v223 offset:0x2e00
	v_exp_f32_e32 v73, v113
	v_exp_f32_e32 v74, v114
	v_exp_f32_e32 v75, v115
	s_waitcnt lgkmcnt(6)
	v_mfma_f32_32x32x16_bf16 v[50:65], v[100:103], v[134:137], v[50:65]
	ds_read_b64_tr_b16 v[134:135], v223 offset:0x3000
	ds_read_b64_tr_b16 v[136:137], v223 offset:0x3800
	v_add_f32_e32 v0, v68, v0
	v_add_f32_e32 v0, v69, v0
	v_add_f32_e32 v0, v70, v0
	v_add_f32_e32 v0, v71, v0
	s_waitcnt lgkmcnt(6)
	v_mfma_f32_32x32x16_bf16 v[34:49], v[100:103], v[138:141], v[34:49]
	ds_read_b64_tr_b16 v[138:139], v223 offset:0x3200
	ds_read_b64_tr_b16 v[140:141], v223 offset:0x3a00
	v_add_f32_e32 v0, v72, v0
	v_add_f32_e32 v0, v73, v0
	v_add_f32_e32 v0, v74, v0
	v_add_f32_e32 v0, v75, v0
	v_mov_b32_e32 v231, v0
	s_waitcnt lgkmcnt(6)
	v_mfma_f32_32x32x16_bf16 v[18:33], v[100:103], v[142:145], v[18:33]
	ds_read_b64_tr_b16 v[142:143], v223 offset:0x3400
	ds_read_b64_tr_b16 v[144:145], v223 offset:0x3c00
	v_cvt_pk_bf16_f32 v104, v68, v69
	v_cvt_pk_bf16_f32 v105, v70, v71
	v_cvt_pk_bf16_f32 v106, v72, v73
	v_cvt_pk_bf16_f32 v107, v74, v75
	v_permlane32_swap_b32_e32 v0, v231
	v_max_f32_e32 v132, v84, v85
	v_max3_f32 v132, v132, v86, v87
	s_waitcnt lgkmcnt(6)
	v_mfma_f32_32x32x16_bf16 v[2:17], v[100:103], v[198:201], v[2:17]
	ds_read_b64_tr_b16 v[198:199], v223 offset:0x3600
	ds_read_b64_tr_b16 v[200:201], v223 offset:0x3e00
	v_permlane32_swap_b32_e32 v104, v106
	v_permlane32_swap_b32_e32 v105, v107
	v_max3_f32 v132, v132, v88, v89
	v_max3_f32 v132, v132, v90, v91
	v_max3_f32 v132, v132, v92, v93
	s_waitcnt lgkmcnt(6)
	v_mfma_f32_32x32x16_bf16 v[50:65], v[104:107], v[134:137], v[50:65]
	v_max3_f32 v132, v132, v94, v95
	v_max3_f32 v132, v132, v96, v97
	v_max3_f32 v132, v132, v98, v99
	v_max3_f32 v132, v132, v116, v117
	v_max3_f32 v132, v132, v118, v119
	s_waitcnt lgkmcnt(4)
	v_mfma_f32_32x32x16_bf16 v[34:49], v[104:107], v[138:141], v[34:49]
	v_max3_f32 v132, v132, v120, v121
	v_max3_f32 v132, v132, v122, v123
	v_max3_f32 v132, v132, v124, v125
	v_max3_f32 v132, v132, v126, v127
	v_max3_f32 v132, v132, v128, v129
	v_max3_f32 v132, v132, v130, v131
	v_mov_b32_e32 v133, v132
	s_waitcnt lgkmcnt(2)
	v_mfma_f32_32x32x16_bf16 v[18:33], v[104:107], v[142:145], v[18:33]
	v_permlane32_swap_b32_e32 v132, v133
	v_max_f32_e32 v100, v132, v133
	v_cmp_ge_f32_e32 vcc, s30, v100
	s_waitcnt lgkmcnt(0)
	v_mfma_f32_32x32x16_bf16 v[2:17], v[104:107], v[198:201], v[2:17]
	s_cmp_lg_u64 vcc, exec
	s_cbranch_scc1 .LBB0_255

; #define SBAR() __builtin_amdgcn_sched_barrier(0)
; #define SLOAD(i, k0) do { sr_[i].vs0 = GLD8(&Vh[(long)((k0) + sr) * LD + sc]); sr_[i].vs1 = GLD8(&Vh[(long)((k0) + 32 + sr) * LD + sc]); \
;     if (DQK == 128) { sr_[i].ks0 = GLD8(&Kh[(long)((k0) + sr) * LD + sc]); sr_[i].ks1 = GLD8(&Kh[(long)((k0) + 32 + sr) * LD + sc]); } \
;     else { sr_[i].ks0 = GLD8(&Kh[(long)((k0) + kr) * LD + kc]); } } while (0)
; #define SWRITE(b, i) do { *(bf16x8*)(V_lds + (b) * SHM_V + vst0) = sr_[i].vs0; *(bf16x8*)(V_lds + (b) * SHM_V + vst1) = sr_[i].vs1; \
;     if (DQK == 128) { *(bf16x8*)(K_lds + (b) * SHM_K + KSWZ(sr, sc * 2)) = sr_[i].ks0; *(bf16x8*)(K_lds + (b) * SHM_K + KSWZ(32 + sr, sc * 2)) = sr_[i].ks1; } \
;     else { *(bf16x8*)(K_lds + (b) * SHM_K + KSWZ64(kr, kc * 2)) = sr_[i].ks0; } } while (0)
; template <bool BIAS, bool VIRT> __device__ __forceinline__ float cinit(int t, int qw0, const float* lut) {
;   if (!BIAS) return 0.f;
;   const int k0 = KVBLK * t, lo = k0 - (qw0 + (VIRT ? 15 : 31)), hi_ = k0 + 63 - qw0;
;   return lo >= 128 ? lut[LUTN - 1] : (hi_ <= -128 ? lut[0] : 0.f);
; }
; template <int DQK, bool BIAS, bool VIRT = false>
; __device__ __forceinline__ void attn_pass(const bf16_t* __restrict__ Qb, const bf16_t* __restrict__ Kh, const bf16_t* __restrict__ Vh, int L, int NT, int qw0, const float* lut, f32x16 (&o)[4], char* lds, int nact) {
;     ...
;   SLOAD(SE, 0); asm volatile("s_waitcnt vmcnt(0)" ::: "memory"); SWRITE(0, SE); __syncthreads();
;   qkt<DQK>(pA0, pA1, K_lds, qr, r32, hi, negm); fixup<BIAS, VIRT>(pA0, pA1, 0, L, qw0, r32, hi, lut); partialSM<true>(pA0, pA1, m_reg, alA, negm, c_cur);
;   SLOAD(SO, KVBLK); if (SDEPTH == 2) { if (2 < NT) SLOAD(SE, 2 * KVBLK); }
;   SWAIT(); SWRITE(1, SO); __syncthreads();
;   for (int j = 1; j + 1 < NT; j += 2) {
;     NEGM(j); SBAR(); qkt<DQK>(pB0, pB1, K_lds + SHM_K, qr, r32, hi, negm);
;     finishSM(pA0, pA1, alA, l_reg, pa0, pa1, pa2, pa3); SBAR();
;     SLOAD(SO, (j + SDEPTH) * KVBLK); SBAR();
;     pv_d0(o, vb0, pa0, pa1, pa2, pa3); fixup<BIAS, VIRT>(pB0, pB1, j, L, qw0, r32, hi, lut); partialSM<false>(pB0, pB1, m_reg, alB, negm, c_cur);
;     __syncthreads(); SWAIT(); SWRITE(0, SE);
;     RESC(alB); __syncthreads();
;     NEGM(j + 1); SBAR(); qkt<DQK>(pA0, pA1, K_lds, qr, r32, hi, negm);
.LBB0_229:
	v_exp_f32_e32 v219, v84
	v_exp_f32_e32 v233, v85
	v_exp_f32_e32 v209, v86
	v_exp_f32_e32 v220, v87
	v_exp_f32_e32 v207, v88
	v_exp_f32_e32 v218, v89
	v_exp_f32_e32 v206, v90
	v_exp_f32_e32 v208, v91
	v_exp_f32_e32 v203, v92
	v_exp_f32_e32 v205, v93
	v_exp_f32_e32 v201, v94
	v_exp_f32_e32 v204, v95
	v_exp_f32_e32 v199, v96
	v_exp_f32_e32 v202, v97
	v_exp_f32_e32 v198, v98
	v_exp_f32_e32 v200, v99
	s_add_i32 s4, s19, 33
	s_cmpk_lt_i32 s4, 0x80
	s_waitcnt lgkmcnt(0)
	s_barrier
	ds_read_b128 v[84:87], v225 offset:36864
	ds_read_b128 v[100:103], v225 offset:32768
	s_cbranch_scc0 .LBB0_233
	s_add_i32 s4, s19, 64
	s_cmpk_gt_i32 s4, 0xff41
	v_mov_b32_e32 v133, 0
	s_cbranch_scc1 .LBB0_232
	v_mov_b32_e32 v68, s38
	ds_read_b32 v133, v68

; __device__ __forceinline__ void finishSM(f32x16& p0, f32x16& p1, float alpha, float& l_reg, bf16x8& pa0, bf16x8& pa1, bf16x8& pa2, bf16x8& pa3) {
; #pragma unroll
;   for (int r = 0; r < 16; ++r) p1[r] = __builtin_amdgcn_exp2f(p1[r]);
;   float ps = 0;
; #pragma unroll
;   for (int r = 0; r < 16; ++r) ps += p0[r];
; #pragma unroll
;   for (int r = 0; r < 16; ++r) ps += p1[r];
;   { auto rr = __builtin_amdgcn_permlane32_swap(__float_as_uint(ps), __float_as_uint(ps), false, false);
;     ps = __uint_as_float(rr[0]) + __uint_as_float(rr[1]); }
;   l_reg = l_reg * alpha + ps;
;     ...
;   PK4(p0, 0, pa0); PK4(p0, 8, pa1); PK4(p1, 0, pa2); PK4(p1, 8, pa3);
; template <int DQK> __device__ __forceinline__ void qkt(f32x16& p0, f32x16& p1, const char* Ks, const bf16x8* qr, int r32, int hi, const f32x16& negm) {
; #pragma unroll
;   for (int d0 = 0; d0 < DQK / 16; ++d0) { const int cb = (d0 * 16 + hi * 8) * 2;
;     const bf16x8 b0 = *reinterpret_cast<const bf16x8*>(Ks + (DQK == 128 ? KSWZ(r32, cb) : KSWZ64(r32, cb)));
;     const bf16x8 b1 = *reinterpret_cast<const bf16x8*>(Ks + (DQK == 128 ? KSWZ(32 + r32, cb) : KSWZ64(32 + r32, cb)));
;     if (d0 == 0) { p0 = __builtin_amdgcn_mfma_f32_32x32x16_bf16(b0, qr[0], negm, 0, 0, 0); p1 = __builtin_amdgcn_mfma_f32_32x32x16_bf16(b1, qr[0], negm, 0, 0, 0); }
;     else { p0 = __builtin_amdgcn_mfma_f32_32x32x16_bf16(b0, qr[d0], p0, 0, 0, 0); p1 = __builtin_amdgcn_mfma_f32_32x32x16_bf16(b1, qr[d0], p1, 0, 0, 0); } }
.LBB0_233:
.LBB0_234:
	v_mov_b32_e32 v68, s39
	ds_read_b32 v133, v68
.LBB0_235:
	s_add_i32 s4, s25, -1
	s_add_i32 s99, s19, 0xffffffa1
	s_cmp_lt_u32 s99, 0xfffffea3
	s_cbranch_scc0 .Lold_h2
	s_add_i32 s99, s18, 64
	s_cmp_le_u32 s99, s47
	s_cbranch_scc0 .Lold_h2
	ds_read_b128 v[88:91], v227 offset:36864
	ds_read_b128 v[134:137], v227 offset:32768
	ds_read_b128 v[138:141], v228 offset:36864
	ds_read_b128 v[142:145], v228 offset:32768
	s_waitcnt lgkmcnt(4)
	v_cmp_neq_f32_e32 vcc, v133, v66
	s_cbranch_vccnz .Lcupd_f2
.Lcret_f2:
	v_mfma_f32_32x32x16_bf16 v[68:83], v[100:103], v[162:165], v[236:251]
	v_mfma_f32_32x32x16_bf16 v[100:115], v[84:87], v[162:165], v[236:251]
	ds_read_b128 v[84:87], v226 offset:36864
	v_add_f32_e32 v235, 0, v219
	v_add_f32_e32 v235, v233, v235
	v_add_f32_e32 v235, v209, v235
	v_add_f32_e32 v235, v220, v235
	v_add_f32_e32 v235, v207, v235
	v_add_f32_e32 v235, v218, v235
	v_add_f32_e32 v235, v206, v235
	v_add_f32_e32 v235, v208, v235
	v_add_f32_e32 v235, v203, v235
	v_add_f32_e32 v235, v205, v235
	s_waitcnt lgkmcnt(3)
	v_mfma_f32_32x32x16_bf16 v[100:115], v[88:91], v[158:161], v[100:115]
	v_add_f32_e32 v235, v201, v235
	v_add_f32_e32 v235, v204, v235
	v_add_f32_e32 v235, v199, v235
	v_add_f32_e32 v235, v202, v235
	v_add_f32_e32 v235, v198, v235
	v_add_f32_e32 v235, v200, v235
	v_mfma_f32_32x32x16_bf16 v[68:83], v[134:137], v[158:161], v[68:83]
	ds_read_b128 v[88:91], v226 offset:32768
	v_cvt_pk_bf16_f32 v92, v219, v233
	v_cvt_pk_bf16_f32 v93, v209, v220
	v_cvt_pk_bf16_f32 v94, v207, v218
	v_cvt_pk_bf16_f32 v95, v206, v208
	v_add_co_u32_e32 v132, vcc, 0x10341000, v148
	s_waitcnt lgkmcnt(2)
	v_mfma_f32_32x32x16_bf16 v[100:115], v[138:141], v[154:157], v[100:115]
	v_cvt_pk_bf16_f32 v96, v203, v205
	v_cvt_pk_bf16_f32 v97, v201, v204
	v_addc_co_u32_e32 v133, vcc, 0, v149, vcc
	v_add_co_u32_e32 v174, vcc, 0x10389000, v148
	v_cvt_pk_bf16_f32 v98, v199, v202
	v_cvt_pk_bf16_f32 v99, v198, v200
	v_addc_co_u32_e32 v175, vcc, 0, v149, vcc
	v_mfma_f32_32x32x16_bf16 v[68:83], v[142:145], v[154:157], v[68:83]
	ds_read_b64_tr_b16 v[134:135], v211 offset:0
	ds_read_b64_tr_b16 v[136:137], v211 offset:0x800
	ds_read_b64_tr_b16 v[138:139], v211 offset:0x200
	ds_read_b64_tr_b16 v[140:141], v211 offset:0xa00
	ds_read_b64_tr_b16 v[142:143], v211 offset:0x400
	ds_read_b64_tr_b16 v[144:145], v211 offset:0xc00
	ds_read_b64_tr_b16 v[146:147], v211 offset:0x600
	ds_read_b64_tr_b16 v[148:149], v211 offset:0xe00
	v_permlane32_swap_b32_e32 v92, v94
	v_permlane32_swap_b32_e32 v93, v95
	v_add_co_u32_e32 v176, vcc, 0x10340000, v196
	s_waitcnt lgkmcnt(8)
	v_mfma_f32_32x32x16_bf16 v[100:115], v[84:87], v[150:153], v[100:115]
	v_permlane32_swap_b32_e32 v96, v98
	v_permlane32_swap_b32_e32 v97, v99
	v_mfma_f32_32x32x16_bf16 v[68:83], v[88:91], v[150:153], v[68:83]
	v_addc_co_u32_e32 v177, vcc, 0, v197, vcc
	s_cmp_ge_u32 s4, s28
	s_cbranch_scc1 .Lnold_h2
	global_load_dwordx4 v[166:169], v[132:133], off
	global_load_dwordx4 v[170:173], v[174:175], off
	global_load_dwordx4 v[174:177], v[176:177], off offset:2048

; #define SBAR() __builtin_amdgcn_sched_barrier(0)
; #define SLOAD(i, k0) do { sr_[i].vs0 = GLD8(&Vh[(long)((k0) + sr) * LD + sc]); sr_[i].vs1 = GLD8(&Vh[(long)((k0) + 32 + sr) * LD + sc]); \
;     if (DQK == 128) { sr_[i].ks0 = GLD8(&Kh[(long)((k0) + sr) * LD + sc]); sr_[i].ks1 = GLD8(&Kh[(long)((k0) + 32 + sr) * LD + sc]); } \
;     else { sr_[i].ks0 = GLD8(&Kh[(long)((k0) + kr) * LD + kc]); } } while (0)
; #define SWRITE(b, i) do { *(bf16x8*)(V_lds + (b) * SHM_V + vst0) = sr_[i].vs0; *(bf16x8*)(V_lds + (b) * SHM_V + vst1) = sr_[i].vs1; \
;     if (DQK == 128) { *(bf16x8*)(K_lds + (b) * SHM_K + KSWZ(sr, sc * 2)) = sr_[i].ks0; *(bf16x8*)(K_lds + (b) * SHM_K + KSWZ(32 + sr, sc * 2)) = sr_[i].ks1; } \
;     else { *(bf16x8*)(K_lds + (b) * SHM_K + KSWZ64(kr, kc * 2)) = sr_[i].ks0; } } while (0)
; #define SWAIT() do { if (SDEPTH == 1) asm volatile("s_waitcnt vmcnt(0)" ::: "memory"); else if (DQK == 128) asm volatile("s_waitcnt vmcnt(4)" ::: "memory"); else asm volatile("s_waitcnt vmcnt(3)" ::: "memory"); } while (0)
; template <int DQK, bool BIAS, bool VIRT = false>
; __device__ __forceinline__ void attn_pass(const bf16_t* __restrict__ Qb, const bf16_t* __restrict__ Kh, const bf16_t* __restrict__ Vh, int L, int NT, int qw0, const float* lut, f32x16 (&o)[4], char* lds, int nact) {
;     ...
;   for (int j = 1; j + 1 < NT; j += 2) {
;     NEGM(j); SBAR(); qkt<DQK>(pB0, pB1, K_lds + SHM_K, qr, r32, hi, negm);
;     finishSM(pA0, pA1, alA, l_reg, pa0, pa1, pa2, pa3); SBAR();
;     SLOAD(SO, (j + SDEPTH) * KVBLK); SBAR();
;     pv_d0(o, vb0, pa0, pa1, pa2, pa3); fixup<BIAS, VIRT>(pB0, pB1, j, L, qw0, r32, hi, lut); partialSM<false>(pB0, pB1, m_reg, alB, negm, c_cur);
;     __syncthreads(); SWAIT(); SWRITE(0, SE);
;     RESC(alB); __syncthreads();
;     NEGM(j + 1); SBAR(); qkt<DQK>(pA0, pA1, K_lds, qr, r32, hi, negm);
;     finishSM(pB0, pB1, alB, l_reg, pa0, pa1, pa2, pa3); SBAR();
;     if (SDEPTH == 1 || j + 3 < NT) SLOAD(SE, (j + 1 + SDEPTH) * KVBLK); SBAR();
;     pv_d0(o, vb0 + SHM_V, pa0, pa1, pa2, pa3); fixup<BIAS, VIRT>(pA0, pA1, j + 1, L, qw0, r32, hi, lut); partialSM<false>(pA0, pA1, m_reg, alA, negm, c_cur);
;     __syncthreads(); SWAIT(); SWRITE(1, SO);
;     RESC(alA); __syncthreads();
;   }
.LBB0_247:
	v_exp_f32_e32 v148, v68
	v_exp_f32_e32 v178, v69
	v_exp_f32_e32 v146, v70
	v_exp_f32_e32 v149, v71
	v_exp_f32_e32 v144, v72
	v_exp_f32_e32 v147, v73
	v_exp_f32_e32 v143, v74
	v_exp_f32_e32 v145, v75
	v_exp_f32_e32 v137, v76
	v_exp_f32_e32 v139, v77
	v_exp_f32_e32 v136, v78
	v_exp_f32_e32 v138, v79
	v_exp_f32_e32 v135, v80
	v_exp_f32_e32 v142, v81
	v_exp_f32_e32 v140, v82
	v_exp_f32_e32 v141, v83
	v_add_f32_e32 v0, v0, v231
	v_fmac_f32_e32 v0, v230, v210
	v_add_f32_e32 v210, v235, v252
	s_addk_i32 s18, 0x80
	s_add_i32 s25, s25, 2
	v_fmac_f32_e32 v210, v0, v232
	v_add_u32_e32 v67, 0x200, v67
	v_lshl_add_u64 v[192:193], v[192:193], 0, s[34:35]
	s_cmp_ge_u32 s25, s46
	v_lshl_add_u64 v[194:195], v[194:195], 0, s[34:35]
	s_waitcnt lgkmcnt(0)
	s_barrier
	s_cbranch_scc1 .Lexit_fix64
	ds_read_b128 v[180:183], v225 offset:53248
	ds_read_b128 v[116:119], v225 offset:49152
	v_mov_b32_e32 v230, v133
	s_add_i32 s19, s11, s18
	s_sub_i32 s4, s19, 31
	s_cmpk_lt_i32 s4, 0x80
	s_cbranch_scc0 .LBB0_216

; #define SBAR() __builtin_amdgcn_sched_barrier(0)
; #define SLOAD(i, k0) do { sr_[i].vs0 = GLD8(&Vh[(long)((k0) + sr) * LD + sc]); sr_[i].vs1 = GLD8(&Vh[(long)((k0) + 32 + sr) * LD + sc]); \
;     if (DQK == 128) { sr_[i].ks0 = GLD8(&Kh[(long)((k0) + sr) * LD + sc]); sr_[i].ks1 = GLD8(&Kh[(long)((k0) + 32 + sr) * LD + sc]); } \
;     else { sr_[i].ks0 = GLD8(&Kh[(long)((k0) + kr) * LD + kc]); } } while (0)
; #define SWRITE(b, i) do { *(bf16x8*)(V_lds + (b) * SHM_V + vst0) = sr_[i].vs0; *(bf16x8*)(V_lds + (b) * SHM_V + vst1) = sr_[i].vs1; \
;     if (DQK == 128) { *(bf16x8*)(K_lds + (b) * SHM_K + KSWZ(sr, sc * 2)) = sr_[i].ks0; *(bf16x8*)(K_lds + (b) * SHM_K + KSWZ(32 + sr, sc * 2)) = sr_[i].ks1; } \
;     else { *(bf16x8*)(K_lds + (b) * SHM_K + KSWZ64(kr, kc * 2)) = sr_[i].ks0; } } while (0)
; #define SWAIT() do { if (SDEPTH == 1) asm volatile("s_waitcnt vmcnt(0)" ::: "memory"); else if (DQK == 128) asm volatile("s_waitcnt vmcnt(4)" ::: "memory"); else asm volatile("s_waitcnt vmcnt(3)" ::: "memory"); } while (0)
; #define NEGM(t) do { if (BIAS) { const float c_ = cinit<BIAS, VIRT>((t), qw0, lut); if (c_ != c_cur) { c_cur = c_; const float nm_ = c_ - m_reg; _Pragma("unroll") for (int r = 0; r < 16; ++r) negm[r] = nm_; } } } while (0)
; template <int DQK, bool BIAS, bool VIRT = false>
; __device__ __forceinline__ void attn_pass(const bf16_t* __restrict__ Qb, const bf16_t* __restrict__ Kh, const bf16_t* __restrict__ Vh, int L, int NT, int qw0, const float* lut, f32x16 (&o)[4], char* lds, int nact) {
;     ...
;   SLOAD(SE, 0); asm volatile("s_waitcnt vmcnt(0)" ::: "memory"); SWRITE(0, SE); __syncthreads();
;   qkt<DQK>(pA0, pA1, K_lds, qr, r32, hi, negm); fixup<BIAS, VIRT>(pA0, pA1, 0, L, qw0, r32, hi, lut); partialSM<true>(pA0, pA1, m_reg, alA, negm, c_cur);
;   SLOAD(SO, KVBLK); if (SDEPTH == 2) { if (2 < NT) SLOAD(SE, 2 * KVBLK); }
;   SWAIT(); SWRITE(1, SO); __syncthreads();
;   for (int j = 1; j + 1 < NT; j += 2) {
;     NEGM(j); SBAR(); qkt<DQK>(pB0, pB1, K_lds + SHM_K, qr, r32, hi, negm);
.Lold_h2:
	s_waitcnt lgkmcnt(0)
	v_mov_b64_e32 v[100:101], v[116:117]
	v_mov_b64_e32 v[102:103], v[118:119]
	v_mov_b64_e32 v[104:105], v[120:121]
	v_mov_b64_e32 v[106:107], v[122:123]
	v_mov_b64_e32 v[108:109], v[124:125]
	v_mov_b64_e32 v[110:111], v[126:127]
	v_mov_b64_e32 v[112:113], v[128:129]
	v_mov_b64_e32 v[114:115], v[130:131]
	s_waitcnt lgkmcnt(0)
	v_cmp_neq_f32_e32 vcc, v133, v66
	s_add_i32 s4, s25, -1
	s_cbranch_vccnz .Lcupd_h2
